# in-proj helpers convert only W_in of the next layer (4096 items) so they finish before the last GEMM round; up phase helpers take the remaining 9216 items
# speedup vs baseline: 1.0010x; 1.0010x over previous
.LBB0_385:
	s_or_b64 exec, exec, s[0:1]
	v_readfirstlane_b32 s57, v2
	s_cmpk_gt_i32 s57, 0xfff
	s_cselect_b64 s[6:7], -1, 0
	s_cmpk_lt_i32 s57, 0x1000
	s_cselect_b32 s15, s57, -1
	s_cmp_lt_i32 s15, 0
	s_cbranch_scc1 .LBB0_433
	s_cmpk_gt_u32 s15, 0xfff
	s_mov_b64 s[8:9], -1
	s_cbranch_scc0 .LBB0_395
	s_cmpk_gt_u32 s15, 0x13ff
	s_cbranch_scc0 .LBB0_392
	s_lshl_b64 s[44:45], s[4:5], 26
	s_lshl_b64 s[46:47], s[4:5], 25
	s_and_b64 vcc, exec, s[6:7]
	s_cbranch_vccz .LBB0_390
	s_add_u32 s10, s20, s44
	s_addc_u32 s11, s21, s45
	v_readlane_b32 s0, v252, 29
	s_add_u32 s0, s0, s46
	v_readlane_b32 s1, v252, 30
	s_addc_u32 s1, s1, s47
	s_mov_b64 s[8:9], 0

.LBB0_408:
	s_cmpk_lt_i32 s9, 0x1000
	s_cselect_b64 s[54:55], -1, 0
	s_and_b64 s[52:53], s[54:55], exec
	s_cselect_b32 s57, s9, -1
	s_cmp_lt_i32 s57, 0
	s_cbranch_scc1 .LBB0_417
	s_cmpk_lt_u32 s57, 0x1000
	s_cbranch_scc1 .LBB0_415
	s_cmpk_gt_u32 s57, 0x13ff
	s_mov_b64 s[50:51], -1
	s_cbranch_scc0 .LBB0_413
	s_andn2_b64 vcc, exec, s[54:55]
	s_cbranch_vccnz .LBB0_431
	s_add_i32 s4, s9, 0xffffec00
	s_movk_i32 s60, 0x800
	s_movk_i32 s7, 0x2000
	s_mov_b64 s[48:49], s[18:19]
	s_mov_b64 s[52:53], s[16:17]
	s_mov_b64 s[50:51], 0

.LBB0_424:
	s_cmpk_lt_i32 s57, 0x1000
	s_cselect_b64 s[54:55], -1, 0
	s_and_b64 s[52:53], s[54:55], exec
	s_cselect_b32 s61, s57, -1
	s_cmp_lt_i32 s61, 0
	s_cbranch_scc1 .LBB0_400
	s_cmpk_lt_u32 s61, 0x1000
	s_cbranch_scc1 .LBB0_398
	s_cmpk_gt_u32 s61, 0x13ff
	s_mov_b64 s[6:7], -1
	s_cbranch_scc0 .LBB0_429
	s_andn2_b64 vcc, exec, s[54:55]
	s_cbranch_vccnz .LBB0_432
	s_add_i32 s8, s57, 0xffffec00
	s_movk_i32 s59, 0x800
	s_movk_i32 s51, 0x2000
	s_mov_b64 s[0:1], s[18:19]
	s_mov_b64 s[52:53], s[16:17]
	s_mov_b64 s[6:7], 0

.LBB0_1400:
	s_or_b64 exec, exec, s[0:1]
	v_readfirstlane_b32 s8, v2
	s_add_i32 s57, s8, 0x1000
	s_cmpk_lt_i32 s8, 0x2400
	s_cselect_b32 s14, s57, -1
	s_cmp_lt_i32 s14, 0
	s_cbranch_scc1 .LBB0_1452
	s_cmpk_gt_u32 s14, 0xfff
	s_mov_b64 s[6:7], -1
	s_cbranch_scc0 .LBB0_1410
	s_cmpk_gt_u32 s14, 0x13ff
	s_cbranch_scc0 .LBB0_1407
	s_lshl_b64 s[46:47], s[4:5], 26
	s_lshl_b64 s[48:49], s[4:5], 25
	s_cmpk_gt_u32 s14, 0x23ff
	s_cbranch_scc0 .LBB0_1405
	s_add_i32 s9, s14, 0xffffdc00
	s_add_u32 s10, s20, s46
	s_addc_u32 s11, s21, s47
	v_readlane_b32 s0, v252, 29
	s_add_u32 s0, s0, s48
	v_readlane_b32 s1, v252, 30
	s_addc_u32 s1, s1, s49
	s_mov_b64 s[6:7], 0

.LBB0_1412:
	s_lshr_b32 s6, s12, 6
	s_add_i32 s56, s8, 0x1008
	s_mulk_i32 s6, 0x4400
	s_lshr_b32 s8, s13, 6
	s_add_i32 s7, s6, 0
	s_ff1_i32_b32 s6, s8
	s_add_i32 s8, s8, -1
	s_and_b32 s8, s8, s9
	s_lshr_b32 s6, s9, s6
	s_lshl_b32 s8, s8, 6
	s_mov_b32 s9, s5
	s_lshl_b32 s6, s6, 6
	s_lshl_b64 s[14:15], s[8:9], 2
	v_lshlrev_b32_e32 v2, 2, v68
	s_waitcnt vmcnt(0)
	v_lshrrev_b32_e32 v133, 4, v68
	s_add_u32 s10, s10, s14
	v_and_b32_e32 v132, 60, v2
	v_or_b32_e32 v64, s6, v133
	s_addc_u32 s11, s11, s15
	v_lshlrev_b32_e32 v34, 2, v132
	v_lshl_add_u64 v[60:61], s[10:11], 0, v[34:35]
	v_or_b32_e32 v34, 32, v64
	v_mad_u64_u32 v[36:37], s[10:11], v34, s13, 0
	v_or_b32_e32 v34, 36, v64
	v_mad_u64_u32 v[38:39], s[10:11], v34, s13, 0
	v_or_b32_e32 v34, 40, v64
	v_mad_u64_u32 v[44:45], s[10:11], v34, s13, 0
	v_or_b32_e32 v34, 44, v64
	v_mad_u64_u32 v[46:47], s[10:11], v34, s13, 0
	v_or_b32_e32 v34, 48, v64
	v_mad_u64_u32 v[52:53], s[10:11], v34, s13, 0
	v_or_b32_e32 v34, 52, v64
	v_mad_u64_u32 v[54:55], s[10:11], v34, s13, 0
	v_or_b32_e32 v34, 56, v64
	v_or_b32_e32 v4, 4, v64
	v_or_b32_e32 v10, 8, v64
	v_or_b32_e32 v12, 12, v64
	v_or_b32_e32 v18, 16, v64
	v_or_b32_e32 v20, 20, v64
	v_or_b32_e32 v26, 24, v64
	v_or_b32_e32 v28, 28, v64
	v_mad_u64_u32 v[62:63], s[10:11], v34, s13, 0
	v_or_b32_e32 v34, 60, v64
	v_mad_u64_u32 v[2:3], s[10:11], v64, s13, 0
	v_mad_u64_u32 v[4:5], s[10:11], v4, s13, 0
	v_mad_u64_u32 v[10:11], s[10:11], v10, s13, 0
	v_mad_u64_u32 v[12:13], s[10:11], v12, s13, 0
	v_mad_u64_u32 v[18:19], s[10:11], v18, s13, 0
	v_mad_u64_u32 v[20:21], s[10:11], v20, s13, 0
	v_mad_u64_u32 v[26:27], s[10:11], v26, s13, 0
	v_mad_u64_u32 v[28:29], s[10:11], v28, s13, 0
	v_mad_u64_u32 v[64:65], s[10:11], v34, s13, 0
	v_lshl_add_u64 v[2:3], v[2:3], 2, v[60:61]
	v_lshl_add_u64 v[6:7], v[4:5], 2, v[60:61]
	v_lshl_add_u64 v[10:11], v[10:11], 2, v[60:61]
	v_lshl_add_u64 v[14:15], v[12:13], 2, v[60:61]
	v_lshl_add_u64 v[18:19], v[18:19], 2, v[60:61]
	v_lshl_add_u64 v[22:23], v[20:21], 2, v[60:61]
	v_lshl_add_u64 v[26:27], v[26:27], 2, v[60:61]
	v_lshl_add_u64 v[30:31], v[28:29], 2, v[60:61]
	v_lshl_add_u64 v[36:37], v[36:37], 2, v[60:61]
	v_lshl_add_u64 v[40:41], v[38:39], 2, v[60:61]
	v_lshl_add_u64 v[44:45], v[44:45], 2, v[60:61]
	v_lshl_add_u64 v[48:49], v[46:47], 2, v[60:61]
	v_lshl_add_u64 v[52:53], v[52:53], 2, v[60:61]
	v_lshl_add_u64 v[56:57], v[54:55], 2, v[60:61]
	v_lshl_add_u64 v[62:63], v[62:63], 2, v[60:61]
	v_lshl_add_u64 v[64:65], v[64:65], 2, v[60:61]
	global_load_dwordx4 v[2:5], v[2:3], off nt
	s_nop 0
	global_load_dwordx4 v[6:9], v[6:7], off nt
	s_nop 0
	global_load_dwordx4 v[10:13], v[10:11], off nt
	s_nop 0
	global_load_dwordx4 v[14:17], v[14:15], off nt
	s_nop 0
	global_load_dwordx4 v[18:21], v[18:19], off nt
	s_nop 0
	global_load_dwordx4 v[22:25], v[22:23], off nt
	s_nop 0
	global_load_dwordx4 v[26:29], v[26:27], off nt
	s_nop 0
	global_load_dwordx4 v[30:33], v[30:31], off nt
	s_nop 0
	global_load_dwordx4 v[36:39], v[36:37], off nt
	s_nop 0
	global_load_dwordx4 v[40:43], v[40:41], off nt
	s_nop 0
	global_load_dwordx4 v[44:47], v[44:45], off nt
	s_nop 0
	global_load_dwordx4 v[48:51], v[48:49], off nt
	s_nop 0
	global_load_dwordx4 v[52:55], v[52:53], off nt
	s_nop 0
	global_load_dwordx4 v[56:59], v[56:57], off nt
	s_nop 0
	global_load_dwordx4 v[60:63], v[62:63], off nt
	s_nop 0
	global_load_dwordx4 v[64:67], v[64:65], off nt
	v_lshlrev_b32_e32 v34, 4, v68
	s_lshl_b32 s10, s4, 6
	s_mov_b32 s11, s5
	v_and_b32_e32 v34, 0xf0, v34
	s_lshl_b64 s[10:11], s[10:11], 2
	v_add_u32_e32 v69, s7, v34
	v_lshlrev_b32_e32 v34, 3, v68
	s_add_u32 s10, s26, s10
	v_lshrrev_b32_e32 v136, 3, v68
	v_and_b32_e32 v34, 56, v34
	s_addc_u32 s11, s27, s11
	v_mul_u32_u24_e32 v68, 0x110, v34
	v_lshlrev_b32_e32 v71, 2, v136
	s_add_u32 s12, s20, s46
	v_readlane_b32 s64, v252, 7
	v_add3_u32 v137, s7, v68, v71
	s_addc_u32 s13, s21, s47
	v_readlane_b32 s7, v252, 29
	v_readlane_b32 s65, v252, 8
	v_readlane_b32 s66, v252, 9
	v_readlane_b32 s67, v252, 10
	v_readlane_b32 s68, v252, 11
	v_readlane_b32 s69, v252, 12
	v_readlane_b32 s70, v252, 13
	v_readlane_b32 s71, v252, 14
	v_readlane_b32 s72, v252, 15
	v_readlane_b32 s73, v252, 16
	v_readlane_b32 s74, v252, 17
	v_readlane_b32 s75, v252, 18
	s_add_u32 s14, s7, s48
	v_readlane_b32 s7, v252, 30
	v_readlane_b32 s76, v252, 19
	v_readlane_b32 s77, v252, 20
	v_readlane_b32 s78, v252, 21
	v_readlane_b32 s79, v252, 22
	s_mov_b64 s[64:65], s[68:69]
	s_addc_u32 s15, s7, s49
	s_mov_b64 s[66:67], s[70:71]
	s_mov_b64 s[68:69], s[72:73]
	s_mov_b64 s[70:71], s[74:75]
	s_mov_b64 s[72:73], s[76:77]
	s_mov_b64 s[74:75], s[78:79]
	s_add_u32 s16, s74, s46
	s_addc_u32 s17, s75, s47
	v_readlane_b32 s7, v252, 27
	s_add_u32 s18, s7, s48
	v_readlane_b32 s7, v252, 28
	s_addc_u32 s19, s7, s49
	s_lshl_b64 s[42:43], s[4:5], 24
	s_add_u32 s42, s72, s42
	s_addc_u32 s43, s73, s43
	s_lshl_b64 s[44:45], s[4:5], 23
	v_readlane_b32 s4, v252, 25
	s_add_u32 s44, s4, s44
	v_readlane_b32 s4, v252, 26
	s_addc_u32 s45, s4, s45
	s_add_u32 s46, s66, s46
	s_addc_u32 s47, s67, s47
	v_readlane_b32 s4, v252, 23
	v_mul_u32_u24_e32 v70, 0x110, v133
	s_add_u32 s48, s4, s48
	v_readlane_b32 s4, v252, 24
	v_readlane_b32 s76, v253, 43
	v_or_b32_e32 v138, 8, v136
	v_or_b32_e32 v139, 16, v136
	v_or_b32_e32 v140, 24, v136
	v_or_b32_e32 v141, 32, v136
	v_or_b32_e32 v142, 40, v136
	v_or_b32_e32 v143, 48, v136
	v_or_b32_e32 v144, 56, v136
	s_addc_u32 s49, s4, s49
	v_lshlrev_b32_e32 v134, 1, v34
	v_add_u32_e32 v145, v69, v70
	v_readlane_b32 s77, v253, 44
	v_readlane_b32 s78, v253, 45
	v_readlane_b32 s79, v253, 46
	v_readlane_b32 s74, v253, 47
	v_readlane_b32 s75, v253, 48
	s_movk_i32 s72, 0x4000
	s_mov_b32 s73, 0xa000
	s_branch .LBB0_1417

.LBB0_1422:
	s_or_b64 exec, exec, s[54:55]
	v_readfirstlane_b32 s7, v34
	s_add_i32 s9, s7, 0x1000
	s_add_i32 s56, s7, 0x1008

.LBB0_1440:
	s_or_b64 exec, exec, s[54:55]
	v_readfirstlane_b32 s7, v34
	s_add_i32 s57, s7, 0x1000
	s_add_i32 s56, s7, 0x1008
